# small_gemm (sample rows split-K pieces) K=1024 reduction: 24 fragment loads all in flight with staged vmcnt instead of ~18 serialized load-wait-2xMFMA steps (4 call sites); stacked on v24
# speedup vs baseline: 1.0334x; 1.0016x over previous
; template <class Epi>
; __device__ __forceinline__ void small_gemm(const Frame& F, const bf16* Aop, const bf16* Bop, const int K_, const Epi& E) {
;     ...
;     if (kw == 128) {
;         bf16x8 af[4][4], bf[2][4];
; #pragma unroll
;         for (int ks = 0; ks < 4; ++ks) {
; #pragma unroll
;             for (int mt = 0; mt < 4; ++mt) af[mt][ks] = *(const bf16x8*)(Ab + (size_t)(16 * mt) * K + 32 * ks);
; #pragma unroll
;             for (int nt = 0; nt < 2; ++nt) bf[nt][ks] = *(const bf16x8*)(Bb + (size_t)(16 * nt) * K + 32 * ks); }
; #pragma unroll
;         for (int ks = 0; ks < 4; ++ks)
; #pragma unroll
;             for (int mt = 0; mt < 4; ++mt)
; #pragma unroll
;                 for (int nt = 0; nt < 2; ++nt) acc[mt][nt] = __builtin_amdgcn_mfma_f32_16x16x32_bf16(bf[nt][ks], af[mt][ks], acc[mt][nt], 0, 0, 0);
.LBB0_1016:
	s_andn2_b64 vcc, exec, s[28:29]
	s_cbranch_vccnz .LBB0_1013
	v_lshl_add_u64 v[84:85], v[68:69], 0, s[26:27]
	v_lshl_add_u64 v[86:87], v[84:85], 0, s[26:27]
	global_load_dwordx4 v[92:95], v[84:85], off
	global_load_dwordx4 v[96:99], v[86:87], off
	global_load_dwordx4 v[100:103], v[66:67], off offset:64
	global_load_dwordx4 v[104:107], v[62:63], off offset:64
	global_load_dwordx4 v[108:111], v[64:65], off offset:64
	global_load_dwordx4 v[112:115], v[68:69], off offset:64
	global_load_dwordx4 v[116:119], v[84:85], off offset:64
	global_load_dwordx4 v[120:123], v[86:87], off offset:64
	global_load_dwordx4 v[124:127], v[66:67], off offset:128
	global_load_dwordx4 v[128:131], v[62:63], off offset:128
	global_load_dwordx4 v[132:135], v[64:65], off offset:128
	global_load_dwordx4 v[136:139], v[68:69], off offset:128
	global_load_dwordx4 v[140:143], v[84:85], off offset:128
	global_load_dwordx4 v[152:155], v[86:87], off offset:128
	global_load_dwordx4 v[156:159], v[66:67], off offset:192
	global_load_dwordx4 v[160:163], v[62:63], off offset:192
	global_load_dwordx4 v[164:167], v[64:65], off offset:192
	global_load_dwordx4 v[172:175], v[68:69], off offset:192
	global_load_dwordx4 v[176:179], v[84:85], off offset:192
	global_load_dwordx4 v[180:183], v[86:87], off offset:192
	s_waitcnt vmcnt(18)
	v_mfma_f32_16x16x32_bf16 v[4:7], v[8:11], v[16:19], 0
	v_mfma_f32_16x16x32_bf16 v[24:27], v[12:15], v[16:19], 0
	v_mfma_f32_16x16x32_bf16 v[28:31], v[8:11], v[20:23], 0
	v_mfma_f32_16x16x32_bf16 v[32:35], v[12:15], v[20:23], 0
	v_mfma_f32_16x16x32_bf16 v[36:39], v[8:11], v[92:95], 0
	v_mfma_f32_16x16x32_bf16 v[40:43], v[12:15], v[92:95], 0
	v_mfma_f32_16x16x32_bf16 v[48:51], v[8:11], v[96:99], 0
	v_mfma_f32_16x16x32_bf16 v[44:47], v[12:15], v[96:99], 0
	s_waitcnt vmcnt(12)
	v_mfma_f32_16x16x32_bf16 v[4:7], v[100:103], v[108:111], v[4:7]
	v_mfma_f32_16x16x32_bf16 v[24:27], v[104:107], v[108:111], v[24:27]
	v_mfma_f32_16x16x32_bf16 v[28:31], v[100:103], v[112:115], v[28:31]
	v_mfma_f32_16x16x32_bf16 v[32:35], v[104:107], v[112:115], v[32:35]
	v_mfma_f32_16x16x32_bf16 v[36:39], v[100:103], v[116:119], v[36:39]
	v_mfma_f32_16x16x32_bf16 v[40:43], v[104:107], v[116:119], v[40:43]
	v_mfma_f32_16x16x32_bf16 v[48:51], v[100:103], v[120:123], v[48:51]
	v_mfma_f32_16x16x32_bf16 v[44:47], v[104:107], v[120:123], v[44:47]
	s_waitcnt vmcnt(6)
	v_mfma_f32_16x16x32_bf16 v[4:7], v[124:127], v[132:135], v[4:7]
	v_mfma_f32_16x16x32_bf16 v[24:27], v[128:131], v[132:135], v[24:27]
	v_mfma_f32_16x16x32_bf16 v[28:31], v[124:127], v[136:139], v[28:31]
	v_mfma_f32_16x16x32_bf16 v[32:35], v[128:131], v[136:139], v[32:35]
	v_mfma_f32_16x16x32_bf16 v[36:39], v[124:127], v[140:143], v[36:39]
	v_mfma_f32_16x16x32_bf16 v[40:43], v[128:131], v[140:143], v[40:43]
	v_mfma_f32_16x16x32_bf16 v[48:51], v[124:127], v[152:155], v[48:51]
	v_mfma_f32_16x16x32_bf16 v[44:47], v[128:131], v[152:155], v[44:47]
	s_waitcnt vmcnt(0)
	v_mfma_f32_16x16x32_bf16 v[4:7], v[156:159], v[164:167], v[4:7]
	v_mfma_f32_16x16x32_bf16 v[24:27], v[160:163], v[164:167], v[24:27]
	v_mfma_f32_16x16x32_bf16 v[28:31], v[156:159], v[172:175], v[28:31]
	v_mfma_f32_16x16x32_bf16 v[32:35], v[160:163], v[172:175], v[32:35]
	v_mfma_f32_16x16x32_bf16 v[36:39], v[156:159], v[176:179], v[36:39]
	v_mfma_f32_16x16x32_bf16 v[40:43], v[160:163], v[176:179], v[40:43]
	v_mfma_f32_16x16x32_bf16 v[48:51], v[156:159], v[180:183], v[48:51]
	v_mfma_f32_16x16x32_bf16 v[44:47], v[160:163], v[180:183], v[44:47]
	s_nop 4
	s_branch .LBB0_1013

; template <class Epi>
; __device__ __forceinline__ void small_gemm(const Frame& F, const bf16* Aop, const bf16* Bop, const int K_, const Epi& E) {
;     ...
;     if (kw == 128) {
;         bf16x8 af[4][4], bf[2][4];
; #pragma unroll
;         for (int ks = 0; ks < 4; ++ks) {
; #pragma unroll
;             for (int mt = 0; mt < 4; ++mt) af[mt][ks] = *(const bf16x8*)(Ab + (size_t)(16 * mt) * K + 32 * ks);
; #pragma unroll
;             for (int nt = 0; nt < 2; ++nt) bf[nt][ks] = *(const bf16x8*)(Bb + (size_t)(16 * nt) * K + 32 * ks); }
; #pragma unroll
;         for (int ks = 0; ks < 4; ++ks)
; #pragma unroll
;             for (int mt = 0; mt < 4; ++mt)
; #pragma unroll
;                 for (int nt = 0; nt < 2; ++nt) acc[mt][nt] = __builtin_amdgcn_mfma_f32_16x16x32_bf16(bf[nt][ks], af[mt][ks], acc[mt][nt], 0, 0, 0);
.LBB0_1023:
	s_andn2_b64 vcc, exec, s[26:27]
	s_cbranch_vccnz .LBB0_1020
	v_lshl_add_u64 v[84:85], v[68:69], 0, s[18:19]
	v_lshl_add_u64 v[86:87], v[84:85], 0, s[18:19]
	global_load_dwordx4 v[92:95], v[84:85], off
	global_load_dwordx4 v[96:99], v[86:87], off
	global_load_dwordx4 v[100:103], v[66:67], off offset:64
	global_load_dwordx4 v[104:107], v[62:63], off offset:64
	global_load_dwordx4 v[108:111], v[64:65], off offset:64
	global_load_dwordx4 v[112:115], v[68:69], off offset:64
	global_load_dwordx4 v[116:119], v[84:85], off offset:64
	global_load_dwordx4 v[120:123], v[86:87], off offset:64
	global_load_dwordx4 v[124:127], v[66:67], off offset:128
	global_load_dwordx4 v[128:131], v[62:63], off offset:128
	global_load_dwordx4 v[132:135], v[64:65], off offset:128
	global_load_dwordx4 v[136:139], v[68:69], off offset:128
	global_load_dwordx4 v[140:143], v[84:85], off offset:128
	global_load_dwordx4 v[152:155], v[86:87], off offset:128
	global_load_dwordx4 v[156:159], v[66:67], off offset:192
	global_load_dwordx4 v[160:163], v[62:63], off offset:192
	global_load_dwordx4 v[164:167], v[64:65], off offset:192
	global_load_dwordx4 v[172:175], v[68:69], off offset:192
	global_load_dwordx4 v[176:179], v[84:85], off offset:192
	global_load_dwordx4 v[180:183], v[86:87], off offset:192
	s_waitcnt vmcnt(18)
	v_mfma_f32_16x16x32_bf16 v[4:7], v[8:11], v[16:19], 0
	v_mfma_f32_16x16x32_bf16 v[24:27], v[12:15], v[16:19], 0
	v_mfma_f32_16x16x32_bf16 v[28:31], v[8:11], v[20:23], 0
	v_mfma_f32_16x16x32_bf16 v[32:35], v[12:15], v[20:23], 0
	v_mfma_f32_16x16x32_bf16 v[36:39], v[8:11], v[92:95], 0
	v_mfma_f32_16x16x32_bf16 v[40:43], v[12:15], v[92:95], 0
	v_mfma_f32_16x16x32_bf16 v[48:51], v[8:11], v[96:99], 0
	v_mfma_f32_16x16x32_bf16 v[44:47], v[12:15], v[96:99], 0
	s_waitcnt vmcnt(12)
	v_mfma_f32_16x16x32_bf16 v[4:7], v[100:103], v[108:111], v[4:7]
	v_mfma_f32_16x16x32_bf16 v[24:27], v[104:107], v[108:111], v[24:27]
	v_mfma_f32_16x16x32_bf16 v[28:31], v[100:103], v[112:115], v[28:31]
	v_mfma_f32_16x16x32_bf16 v[32:35], v[104:107], v[112:115], v[32:35]
	v_mfma_f32_16x16x32_bf16 v[36:39], v[100:103], v[116:119], v[36:39]
	v_mfma_f32_16x16x32_bf16 v[40:43], v[104:107], v[116:119], v[40:43]
	v_mfma_f32_16x16x32_bf16 v[48:51], v[100:103], v[120:123], v[48:51]
	v_mfma_f32_16x16x32_bf16 v[44:47], v[104:107], v[120:123], v[44:47]
	s_waitcnt vmcnt(6)
	v_mfma_f32_16x16x32_bf16 v[4:7], v[124:127], v[132:135], v[4:7]
	v_mfma_f32_16x16x32_bf16 v[24:27], v[128:131], v[132:135], v[24:27]
	v_mfma_f32_16x16x32_bf16 v[28:31], v[124:127], v[136:139], v[28:31]
	v_mfma_f32_16x16x32_bf16 v[32:35], v[128:131], v[136:139], v[32:35]
	v_mfma_f32_16x16x32_bf16 v[36:39], v[124:127], v[140:143], v[36:39]
	v_mfma_f32_16x16x32_bf16 v[40:43], v[128:131], v[140:143], v[40:43]
	v_mfma_f32_16x16x32_bf16 v[48:51], v[124:127], v[152:155], v[48:51]
	v_mfma_f32_16x16x32_bf16 v[44:47], v[128:131], v[152:155], v[44:47]
	s_waitcnt vmcnt(0)
	v_mfma_f32_16x16x32_bf16 v[4:7], v[156:159], v[164:167], v[4:7]
	v_mfma_f32_16x16x32_bf16 v[24:27], v[160:163], v[164:167], v[24:27]
	v_mfma_f32_16x16x32_bf16 v[28:31], v[156:159], v[172:175], v[28:31]
	v_mfma_f32_16x16x32_bf16 v[32:35], v[160:163], v[172:175], v[32:35]
	v_mfma_f32_16x16x32_bf16 v[36:39], v[156:159], v[176:179], v[36:39]
	v_mfma_f32_16x16x32_bf16 v[40:43], v[160:163], v[176:179], v[40:43]
	v_mfma_f32_16x16x32_bf16 v[48:51], v[156:159], v[180:183], v[48:51]
	v_mfma_f32_16x16x32_bf16 v[44:47], v[160:163], v[180:183], v[44:47]
	s_nop 4
	s_branch .LBB0_1020

; template <class Epi>
; __device__ __forceinline__ void small_gemm(const Frame& F, const bf16* Aop, const bf16* Bop, const int K_, const Epi& E) {
;     ...
;     if (kw == 128) {
;         bf16x8 af[4][4], bf[2][4];
; #pragma unroll
;         for (int ks = 0; ks < 4; ++ks) {
; #pragma unroll
;             for (int mt = 0; mt < 4; ++mt) af[mt][ks] = *(const bf16x8*)(Ab + (size_t)(16 * mt) * K + 32 * ks);
; #pragma unroll
;             for (int nt = 0; nt < 2; ++nt) bf[nt][ks] = *(const bf16x8*)(Bb + (size_t)(16 * nt) * K + 32 * ks); }
; #pragma unroll
;         for (int ks = 0; ks < 4; ++ks)
; #pragma unroll
;             for (int mt = 0; mt < 4; ++mt)
; #pragma unroll
;                 for (int nt = 0; nt < 2; ++nt) acc[mt][nt] = __builtin_amdgcn_mfma_f32_16x16x32_bf16(bf[nt][ks], af[mt][ks], acc[mt][nt], 0, 0, 0);
.LBB0_1106:
	s_andn2_b64 vcc, exec, s[18:19]
	s_cbranch_vccnz .LBB0_1103
	v_lshl_add_u64 v[84:85], v[66:67], 0, s[16:17]
	v_lshl_add_u64 v[86:87], v[84:85], 0, s[16:17]
	global_load_dwordx4 v[92:95], v[84:85], off
	global_load_dwordx4 v[96:99], v[86:87], off
	global_load_dwordx4 v[100:103], v[64:65], off offset:64
	global_load_dwordx4 v[104:107], v[60:61], off offset:64
	global_load_dwordx4 v[108:111], v[62:63], off offset:64
	global_load_dwordx4 v[112:115], v[66:67], off offset:64
	global_load_dwordx4 v[116:119], v[84:85], off offset:64
	global_load_dwordx4 v[120:123], v[86:87], off offset:64
	global_load_dwordx4 v[124:127], v[64:65], off offset:128
	global_load_dwordx4 v[128:131], v[60:61], off offset:128
	global_load_dwordx4 v[132:135], v[62:63], off offset:128
	global_load_dwordx4 v[136:139], v[66:67], off offset:128
	global_load_dwordx4 v[140:143], v[84:85], off offset:128
	global_load_dwordx4 v[152:155], v[86:87], off offset:128
	global_load_dwordx4 v[156:159], v[64:65], off offset:192
	global_load_dwordx4 v[160:163], v[60:61], off offset:192
	global_load_dwordx4 v[164:167], v[62:63], off offset:192
	global_load_dwordx4 v[172:175], v[66:67], off offset:192
	global_load_dwordx4 v[176:179], v[84:85], off offset:192
	global_load_dwordx4 v[180:183], v[86:87], off offset:192
	s_waitcnt vmcnt(18)
	v_mfma_f32_16x16x32_bf16 v[4:7], v[8:11], v[16:19], 0
	v_mfma_f32_16x16x32_bf16 v[24:27], v[12:15], v[16:19], 0
	v_mfma_f32_16x16x32_bf16 v[28:31], v[8:11], v[20:23], 0
	v_mfma_f32_16x16x32_bf16 v[32:35], v[12:15], v[20:23], 0
	v_mfma_f32_16x16x32_bf16 v[36:39], v[8:11], v[92:95], 0
	v_mfma_f32_16x16x32_bf16 v[40:43], v[12:15], v[92:95], 0
	v_mfma_f32_16x16x32_bf16 v[48:51], v[8:11], v[96:99], 0
	v_mfma_f32_16x16x32_bf16 v[44:47], v[12:15], v[96:99], 0
	s_waitcnt vmcnt(12)
	v_mfma_f32_16x16x32_bf16 v[4:7], v[100:103], v[108:111], v[4:7]
	v_mfma_f32_16x16x32_bf16 v[24:27], v[104:107], v[108:111], v[24:27]
	v_mfma_f32_16x16x32_bf16 v[28:31], v[100:103], v[112:115], v[28:31]
	v_mfma_f32_16x16x32_bf16 v[32:35], v[104:107], v[112:115], v[32:35]
	v_mfma_f32_16x16x32_bf16 v[36:39], v[100:103], v[116:119], v[36:39]
	v_mfma_f32_16x16x32_bf16 v[40:43], v[104:107], v[116:119], v[40:43]
	v_mfma_f32_16x16x32_bf16 v[48:51], v[100:103], v[120:123], v[48:51]
	v_mfma_f32_16x16x32_bf16 v[44:47], v[104:107], v[120:123], v[44:47]
	s_waitcnt vmcnt(6)
	v_mfma_f32_16x16x32_bf16 v[4:7], v[124:127], v[132:135], v[4:7]
	v_mfma_f32_16x16x32_bf16 v[24:27], v[128:131], v[132:135], v[24:27]
	v_mfma_f32_16x16x32_bf16 v[28:31], v[124:127], v[136:139], v[28:31]
	v_mfma_f32_16x16x32_bf16 v[32:35], v[128:131], v[136:139], v[32:35]
	v_mfma_f32_16x16x32_bf16 v[36:39], v[124:127], v[140:143], v[36:39]
	v_mfma_f32_16x16x32_bf16 v[40:43], v[128:131], v[140:143], v[40:43]
	v_mfma_f32_16x16x32_bf16 v[48:51], v[124:127], v[152:155], v[48:51]
	v_mfma_f32_16x16x32_bf16 v[44:47], v[128:131], v[152:155], v[44:47]
	s_waitcnt vmcnt(0)
	v_mfma_f32_16x16x32_bf16 v[4:7], v[156:159], v[164:167], v[4:7]
	v_mfma_f32_16x16x32_bf16 v[24:27], v[160:163], v[164:167], v[24:27]
	v_mfma_f32_16x16x32_bf16 v[28:31], v[156:159], v[172:175], v[28:31]
	v_mfma_f32_16x16x32_bf16 v[32:35], v[160:163], v[172:175], v[32:35]
	v_mfma_f32_16x16x32_bf16 v[36:39], v[156:159], v[176:179], v[36:39]
	v_mfma_f32_16x16x32_bf16 v[40:43], v[160:163], v[176:179], v[40:43]
	v_mfma_f32_16x16x32_bf16 v[48:51], v[156:159], v[180:183], v[48:51]
	v_mfma_f32_16x16x32_bf16 v[44:47], v[160:163], v[180:183], v[44:47]
	s_nop 4
	s_branch .LBB0_1103

; template <class Epi>
; __device__ __forceinline__ void small_gemm(const Frame& F, const bf16* Aop, const bf16* Bop, const int K_, const Epi& E) {
;     ...
;     if (kw == 128) {
;         bf16x8 af[4][4], bf[2][4];
; #pragma unroll
;         for (int ks = 0; ks < 4; ++ks) {
; #pragma unroll
;             for (int mt = 0; mt < 4; ++mt) af[mt][ks] = *(const bf16x8*)(Ab + (size_t)(16 * mt) * K + 32 * ks);
; #pragma unroll
;             for (int nt = 0; nt < 2; ++nt) bf[nt][ks] = *(const bf16x8*)(Bb + (size_t)(16 * nt) * K + 32 * ks); }
; #pragma unroll
;         for (int ks = 0; ks < 4; ++ks)
; #pragma unroll
;             for (int mt = 0; mt < 4; ++mt)
; #pragma unroll
;                 for (int nt = 0; nt < 2; ++nt) acc[mt][nt] = __builtin_amdgcn_mfma_f32_16x16x32_bf16(bf[nt][ks], af[mt][ks], acc[mt][nt], 0, 0, 0);
.LBB0_1609:
	s_andn2_b64 vcc, exec, s[16:17]
	s_cbranch_vccnz .LBB0_1606
	v_lshl_add_u64 v[84:85], v[68:69], 0, s[12:13]
	v_lshl_add_u64 v[86:87], v[84:85], 0, s[12:13]
	global_load_dwordx4 v[92:95], v[84:85], off
	global_load_dwordx4 v[96:99], v[86:87], off
	global_load_dwordx4 v[100:103], v[66:67], off offset:64
	global_load_dwordx4 v[104:107], v[62:63], off offset:64
	global_load_dwordx4 v[108:111], v[64:65], off offset:64
	global_load_dwordx4 v[112:115], v[68:69], off offset:64
	global_load_dwordx4 v[116:119], v[84:85], off offset:64
	global_load_dwordx4 v[120:123], v[86:87], off offset:64
	global_load_dwordx4 v[124:127], v[66:67], off offset:128
	global_load_dwordx4 v[128:131], v[62:63], off offset:128
	global_load_dwordx4 v[132:135], v[64:65], off offset:128
	global_load_dwordx4 v[136:139], v[68:69], off offset:128
	global_load_dwordx4 v[140:143], v[84:85], off offset:128
	global_load_dwordx4 v[152:155], v[86:87], off offset:128
	global_load_dwordx4 v[156:159], v[66:67], off offset:192
	global_load_dwordx4 v[160:163], v[62:63], off offset:192
	global_load_dwordx4 v[164:167], v[64:65], off offset:192
	global_load_dwordx4 v[172:175], v[68:69], off offset:192
	global_load_dwordx4 v[176:179], v[84:85], off offset:192
	global_load_dwordx4 v[180:183], v[86:87], off offset:192
	s_waitcnt vmcnt(18)
	v_mfma_f32_16x16x32_bf16 v[4:7], v[8:11], v[16:19], 0
	v_mfma_f32_16x16x32_bf16 v[24:27], v[12:15], v[16:19], 0
	v_mfma_f32_16x16x32_bf16 v[28:31], v[8:11], v[20:23], 0
	v_mfma_f32_16x16x32_bf16 v[32:35], v[12:15], v[20:23], 0
	v_mfma_f32_16x16x32_bf16 v[36:39], v[8:11], v[92:95], 0
	v_mfma_f32_16x16x32_bf16 v[40:43], v[12:15], v[92:95], 0
	v_mfma_f32_16x16x32_bf16 v[48:51], v[8:11], v[96:99], 0
	v_mfma_f32_16x16x32_bf16 v[44:47], v[12:15], v[96:99], 0
	s_waitcnt vmcnt(12)
	v_mfma_f32_16x16x32_bf16 v[4:7], v[100:103], v[108:111], v[4:7]
	v_mfma_f32_16x16x32_bf16 v[24:27], v[104:107], v[108:111], v[24:27]
	v_mfma_f32_16x16x32_bf16 v[28:31], v[100:103], v[112:115], v[28:31]
	v_mfma_f32_16x16x32_bf16 v[32:35], v[104:107], v[112:115], v[32:35]
	v_mfma_f32_16x16x32_bf16 v[36:39], v[100:103], v[116:119], v[36:39]
	v_mfma_f32_16x16x32_bf16 v[40:43], v[104:107], v[116:119], v[40:43]
	v_mfma_f32_16x16x32_bf16 v[48:51], v[100:103], v[120:123], v[48:51]
	v_mfma_f32_16x16x32_bf16 v[44:47], v[104:107], v[120:123], v[44:47]
	s_waitcnt vmcnt(6)
	v_mfma_f32_16x16x32_bf16 v[4:7], v[124:127], v[132:135], v[4:7]
	v_mfma_f32_16x16x32_bf16 v[24:27], v[128:131], v[132:135], v[24:27]
	v_mfma_f32_16x16x32_bf16 v[28:31], v[124:127], v[136:139], v[28:31]
	v_mfma_f32_16x16x32_bf16 v[32:35], v[128:131], v[136:139], v[32:35]
	v_mfma_f32_16x16x32_bf16 v[36:39], v[124:127], v[140:143], v[36:39]
	v_mfma_f32_16x16x32_bf16 v[40:43], v[128:131], v[140:143], v[40:43]
	v_mfma_f32_16x16x32_bf16 v[48:51], v[124:127], v[152:155], v[48:51]
	v_mfma_f32_16x16x32_bf16 v[44:47], v[128:131], v[152:155], v[44:47]
	s_waitcnt vmcnt(0)
	v_mfma_f32_16x16x32_bf16 v[4:7], v[156:159], v[164:167], v[4:7]
	v_mfma_f32_16x16x32_bf16 v[24:27], v[160:163], v[164:167], v[24:27]
	v_mfma_f32_16x16x32_bf16 v[28:31], v[156:159], v[172:175], v[28:31]
	v_mfma_f32_16x16x32_bf16 v[32:35], v[160:163], v[172:175], v[32:35]
	v_mfma_f32_16x16x32_bf16 v[36:39], v[156:159], v[176:179], v[36:39]
	v_mfma_f32_16x16x32_bf16 v[40:43], v[160:163], v[176:179], v[40:43]
	v_mfma_f32_16x16x32_bf16 v[48:51], v[156:159], v[180:183], v[48:51]
	v_mfma_f32_16x16x32_bf16 v[44:47], v[160:163], v[180:183], v[44:47]
	s_nop 4
	s_branch .LBB0_1606
